# attention: four K fragments read ahead of the tile barrier
# speedup vs baseline: 1.0053x; 1.0053x over previous
.LBB0_168:
	ds_read_b128 v[98:101], v239 offset:16384
	ds_read_b128 v[114:117], v239 offset:24576
	ds_read_b128 v[118:121], v240 offset:16384
	ds_read_b128 v[122:125], v240 offset:24576
	s_barrier

.LBB0_185:
	ds_read_b128 v[126:129], v244 offset:16384
	s_waitcnt lgkmcnt(1)
	v_mfma_f32_32x32x16_bf16 v[82:97], v[98:101], v[146:149], v[66:81]
	v_mfma_f32_32x32x16_bf16 v[98:113], v[114:117], v[146:149], v[66:81]
	ds_read_b128 v[114:117], v241 offset:16384
	v_mfma_f32_32x32x16_bf16 v[82:97], v[118:121], v[150:153], v[82:97]
	ds_read_b128 v[118:121], v241 offset:24576
	s_waitcnt lgkmcnt(0)
	v_mfma_f32_32x32x16_bf16 v[98:113], v[122:125], v[150:153], v[98:113]
	ds_read_b128 v[122:125], v243 offset:16384
	v_mfma_f32_32x32x16_bf16 v[82:97], v[114:117], v[154:157], v[82:97]
	ds_read_b128 v[114:117], v243 offset:24576
	v_mfma_f32_32x32x16_bf16 v[98:113], v[118:121], v[154:157], v[98:113]
	s_waitcnt lgkmcnt(0)
	v_mfma_f32_32x32x16_bf16 v[82:97], v[122:125], v[158:161], v[82:97]
	v_mfma_f32_32x32x16_bf16 v[98:113], v[114:117], v[158:161], v[98:113]
	s_nop 0
	ds_read_b128 v[122:125], v244 offset:20480
	ds_read_b128 v[118:121], v244 offset:24576
	ds_read_b128 v[114:117], v244 offset:28672
	s_add_i32 s22, s21, 64
	s_cmp_le_u32 s22, s20
	s_cbranch_scc0 .Lnear_u1e

.LBB0_208:
	ds_read_b128 v[98:101], v239 offset:32768
	ds_read_b128 v[114:117], v239 offset:40960
	ds_read_b128 v[118:121], v240 offset:32768
	ds_read_b128 v[122:125], v240 offset:40960
	s_barrier

.LBB0_225:
	ds_read_b128 v[126:129], v244 offset:32768
	s_waitcnt lgkmcnt(1)
	v_mfma_f32_32x32x16_bf16 v[82:97], v[98:101], v[146:149], v[66:81]
	v_mfma_f32_32x32x16_bf16 v[98:113], v[114:117], v[146:149], v[66:81]
	ds_read_b128 v[114:117], v241 offset:32768
	v_mfma_f32_32x32x16_bf16 v[82:97], v[118:121], v[150:153], v[82:97]
	ds_read_b128 v[118:121], v241 offset:40960
	s_waitcnt lgkmcnt(0)
	v_mfma_f32_32x32x16_bf16 v[98:113], v[122:125], v[150:153], v[98:113]
	ds_read_b128 v[122:125], v243 offset:32768
	v_mfma_f32_32x32x16_bf16 v[82:97], v[114:117], v[154:157], v[82:97]
	ds_read_b128 v[114:117], v243 offset:40960
	v_mfma_f32_32x32x16_bf16 v[98:113], v[118:121], v[154:157], v[98:113]
	s_waitcnt lgkmcnt(0)
	v_mfma_f32_32x32x16_bf16 v[82:97], v[122:125], v[158:161], v[82:97]
	v_mfma_f32_32x32x16_bf16 v[98:113], v[114:117], v[158:161], v[98:113]
	s_nop 0
	ds_read_b128 v[122:125], v244 offset:36864
	ds_read_b128 v[118:121], v244 offset:40960
	ds_read_b128 v[114:117], v244 offset:45056
	s_add_i32 s26, s21, 0x80
	s_cmp_le_u32 s26, s20
	s_cbranch_scc0 .Lnear_u1o

.Lr1u1_LBB0_168:
	ds_read_b128 v[98:101], v239
	ds_read_b128 v[114:117], v239 offset:8192
	ds_read_b128 v[118:121], v240
	ds_read_b128 v[122:125], v240 offset:8192
	s_barrier

.Lr1u1_LBB0_185:
	ds_read_b128 v[126:129], v244 offset:49152
	s_waitcnt lgkmcnt(1)
	v_mfma_f32_32x32x16_bf16 v[82:97], v[98:101], v[146:149], v[66:81]
	v_mfma_f32_32x32x16_bf16 v[98:113], v[114:117], v[146:149], v[66:81]
	ds_read_b128 v[114:117], v241
	v_mfma_f32_32x32x16_bf16 v[82:97], v[118:121], v[150:153], v[82:97]
	ds_read_b128 v[118:121], v241 offset:8192
	s_waitcnt lgkmcnt(0)
	v_mfma_f32_32x32x16_bf16 v[98:113], v[122:125], v[150:153], v[98:113]
	ds_read_b128 v[122:125], v243
	v_mfma_f32_32x32x16_bf16 v[82:97], v[114:117], v[154:157], v[82:97]
	ds_read_b128 v[114:117], v243 offset:8192
	v_mfma_f32_32x32x16_bf16 v[98:113], v[118:121], v[154:157], v[98:113]
	s_waitcnt lgkmcnt(0)
	v_mfma_f32_32x32x16_bf16 v[82:97], v[122:125], v[158:161], v[82:97]
	v_mfma_f32_32x32x16_bf16 v[98:113], v[114:117], v[158:161], v[98:113]
	s_nop 0
	ds_read_b128 v[122:125], v244 offset:53248
	ds_read_b128 v[118:121], v244 offset:57344
	ds_read_b128 v[114:117], v244 offset:61440
	s_add_i32 s22, s21, 64
	s_cmp_le_u32 s22, s20
	s_cbranch_scc0 .Lr1u1_Lnear_u1e

.Lr1u1_LBB0_225:
	ds_read_b128 v[126:129], v244 offset:16384
	s_waitcnt lgkmcnt(1)
	v_mfma_f32_32x32x16_bf16 v[82:97], v[98:101], v[146:149], v[66:81]
	v_mfma_f32_32x32x16_bf16 v[98:113], v[114:117], v[146:149], v[66:81]
	ds_read_b128 v[114:117], v241 offset:16384
	v_mfma_f32_32x32x16_bf16 v[82:97], v[118:121], v[150:153], v[82:97]
	ds_read_b128 v[118:121], v241 offset:24576
	s_waitcnt lgkmcnt(0)
	v_mfma_f32_32x32x16_bf16 v[98:113], v[122:125], v[150:153], v[98:113]
	ds_read_b128 v[122:125], v243 offset:16384
	v_mfma_f32_32x32x16_bf16 v[82:97], v[114:117], v[154:157], v[82:97]
	ds_read_b128 v[114:117], v243 offset:24576
	v_mfma_f32_32x32x16_bf16 v[98:113], v[118:121], v[154:157], v[98:113]
	s_waitcnt lgkmcnt(0)
	v_mfma_f32_32x32x16_bf16 v[82:97], v[122:125], v[158:161], v[82:97]
	v_mfma_f32_32x32x16_bf16 v[98:113], v[114:117], v[158:161], v[98:113]
	s_nop 0
	ds_read_b128 v[122:125], v244 offset:20480
	ds_read_b128 v[118:121], v244 offset:24576
	ds_read_b128 v[114:117], v244 offset:28672
	s_add_i32 s26, s21, 0x80
	s_cmp_le_u32 s26, s20
	s_cbranch_scc0 .Lr1u1_Lnear_u1o

.Lr2u1_LBB0_185:
	ds_read_b128 v[126:129], v244 offset:32768
	s_waitcnt lgkmcnt(1)
	v_mfma_f32_32x32x16_bf16 v[82:97], v[98:101], v[146:149], v[66:81]
	v_mfma_f32_32x32x16_bf16 v[98:113], v[114:117], v[146:149], v[66:81]
	ds_read_b128 v[114:117], v241 offset:32768
	v_mfma_f32_32x32x16_bf16 v[82:97], v[118:121], v[150:153], v[82:97]
	ds_read_b128 v[118:121], v241 offset:40960
	s_waitcnt lgkmcnt(0)
	v_mfma_f32_32x32x16_bf16 v[98:113], v[122:125], v[150:153], v[98:113]
	ds_read_b128 v[122:125], v243 offset:32768
	v_mfma_f32_32x32x16_bf16 v[82:97], v[114:117], v[154:157], v[82:97]
	ds_read_b128 v[114:117], v243 offset:40960
	v_mfma_f32_32x32x16_bf16 v[98:113], v[118:121], v[154:157], v[98:113]
	s_waitcnt lgkmcnt(0)
	v_mfma_f32_32x32x16_bf16 v[82:97], v[122:125], v[158:161], v[82:97]
	v_mfma_f32_32x32x16_bf16 v[98:113], v[114:117], v[158:161], v[98:113]
	s_nop 0
	ds_read_b128 v[122:125], v244 offset:36864
	ds_read_b128 v[118:121], v244 offset:40960
	ds_read_b128 v[114:117], v244 offset:45056
	s_add_i32 s22, s21, 64
	s_cmp_le_u32 s22, s20
	s_cbranch_scc0 .Lr2u1_Lnear_u1e

.Lr2u1_LBB0_225:
	ds_read_b128 v[126:129], v244 offset:49152
	s_waitcnt lgkmcnt(1)
	v_mfma_f32_32x32x16_bf16 v[82:97], v[98:101], v[146:149], v[66:81]
	v_mfma_f32_32x32x16_bf16 v[98:113], v[114:117], v[146:149], v[66:81]
	ds_read_b128 v[114:117], v241
	v_mfma_f32_32x32x16_bf16 v[82:97], v[118:121], v[150:153], v[82:97]
	ds_read_b128 v[118:121], v241 offset:8192
	s_waitcnt lgkmcnt(0)
	v_mfma_f32_32x32x16_bf16 v[98:113], v[122:125], v[150:153], v[98:113]
	ds_read_b128 v[122:125], v243
	v_mfma_f32_32x32x16_bf16 v[82:97], v[114:117], v[154:157], v[82:97]
	ds_read_b128 v[114:117], v243 offset:8192
	v_mfma_f32_32x32x16_bf16 v[98:113], v[118:121], v[154:157], v[98:113]
	s_waitcnt lgkmcnt(0)
	v_mfma_f32_32x32x16_bf16 v[82:97], v[122:125], v[158:161], v[82:97]
	v_mfma_f32_32x32x16_bf16 v[98:113], v[114:117], v[158:161], v[98:113]
	s_nop 0
	ds_read_b128 v[122:125], v244 offset:53248
	ds_read_b128 v[118:121], v244 offset:57344
	ds_read_b128 v[114:117], v244 offset:61440
	s_add_i32 s26, s21, 0x80
	s_cmp_le_u32 s26, s20
	s_cbranch_scc0 .Lr2u1_Lnear_u1o

.LBB0_288:
	ds_read_b128 v[126:129], v245 offset:16384
	s_waitcnt lgkmcnt(1)
	v_mfma_f32_32x32x16_bf16 v[82:97], v[98:101], v[146:149], v[66:81]
	v_mfma_f32_32x32x16_bf16 v[98:113], v[114:117], v[146:149], v[66:81]
	ds_read_b128 v[114:117], v241 offset:16384
	v_mfma_f32_32x32x16_bf16 v[82:97], v[118:121], v[150:153], v[82:97]
	ds_read_b128 v[118:121], v241 offset:24576
	s_waitcnt lgkmcnt(0)
	v_mfma_f32_32x32x16_bf16 v[98:113], v[122:125], v[150:153], v[98:113]
	ds_read_b128 v[122:125], v242 offset:16384
	v_mfma_f32_32x32x16_bf16 v[82:97], v[114:117], v[154:157], v[82:97]
	ds_read_b128 v[114:117], v242 offset:24576
	v_mfma_f32_32x32x16_bf16 v[98:113], v[118:121], v[154:157], v[98:113]
	s_waitcnt lgkmcnt(0)
	v_mfma_f32_32x32x16_bf16 v[82:97], v[122:125], v[158:161], v[82:97]
	v_mfma_f32_32x32x16_bf16 v[98:113], v[114:117], v[158:161], v[98:113]
	s_nop 0
	ds_read_b128 v[122:125], v245 offset:20480
	ds_read_b128 v[118:121], v245 offset:24576
	ds_read_b128 v[114:117], v245 offset:28672
	s_cmp_le_u32 s20, s16
	s_cbranch_scc0 .Lnear_u2e

.LBB0_328:
	ds_read_b128 v[126:129], v245 offset:32768
	s_waitcnt lgkmcnt(1)
	v_mfma_f32_32x32x16_bf16 v[82:97], v[98:101], v[146:149], v[66:81]
	v_mfma_f32_32x32x16_bf16 v[98:113], v[114:117], v[146:149], v[66:81]
	ds_read_b128 v[114:117], v241 offset:32768
	v_mfma_f32_32x32x16_bf16 v[82:97], v[118:121], v[150:153], v[82:97]
	ds_read_b128 v[118:121], v241 offset:40960
	s_waitcnt lgkmcnt(0)
	v_mfma_f32_32x32x16_bf16 v[98:113], v[122:125], v[150:153], v[98:113]
	ds_read_b128 v[122:125], v242 offset:32768
	v_mfma_f32_32x32x16_bf16 v[82:97], v[114:117], v[154:157], v[82:97]
	ds_read_b128 v[114:117], v242 offset:40960
	v_mfma_f32_32x32x16_bf16 v[98:113], v[118:121], v[154:157], v[98:113]
	s_waitcnt lgkmcnt(0)
	v_mfma_f32_32x32x16_bf16 v[82:97], v[122:125], v[158:161], v[82:97]
	v_mfma_f32_32x32x16_bf16 v[98:113], v[114:117], v[158:161], v[98:113]
	s_nop 0
	ds_read_b128 v[122:125], v245 offset:36864
	ds_read_b128 v[118:121], v245 offset:40960
	ds_read_b128 v[114:117], v245 offset:45056
	s_add_i32 s26, s20, 64
	s_cmp_le_u32 s26, s16
	s_cbranch_scc0 .Lnear_u2o

.Lr1u2_LBB0_288:
	ds_read_b128 v[126:129], v245 offset:49152
	s_waitcnt lgkmcnt(1)
	v_mfma_f32_32x32x16_bf16 v[82:97], v[98:101], v[146:149], v[66:81]
	v_mfma_f32_32x32x16_bf16 v[98:113], v[114:117], v[146:149], v[66:81]
	ds_read_b128 v[114:117], v241
	v_mfma_f32_32x32x16_bf16 v[82:97], v[118:121], v[150:153], v[82:97]
	ds_read_b128 v[118:121], v241 offset:8192
	s_waitcnt lgkmcnt(0)
	v_mfma_f32_32x32x16_bf16 v[98:113], v[122:125], v[150:153], v[98:113]
	ds_read_b128 v[122:125], v242
	v_mfma_f32_32x32x16_bf16 v[82:97], v[114:117], v[154:157], v[82:97]
	ds_read_b128 v[114:117], v242 offset:8192
	v_mfma_f32_32x32x16_bf16 v[98:113], v[118:121], v[154:157], v[98:113]
	s_waitcnt lgkmcnt(0)
	v_mfma_f32_32x32x16_bf16 v[82:97], v[122:125], v[158:161], v[82:97]
	v_mfma_f32_32x32x16_bf16 v[98:113], v[114:117], v[158:161], v[98:113]
	s_nop 0
	ds_read_b128 v[122:125], v245 offset:53248
	ds_read_b128 v[118:121], v245 offset:57344
	ds_read_b128 v[114:117], v245 offset:61440
	s_cmp_le_u32 s20, s16
	s_cbranch_scc0 .Lr1u2_Lnear_u2e

.Lr1u2_LBB0_328:
	ds_read_b128 v[126:129], v245 offset:16384
	s_waitcnt lgkmcnt(1)
	v_mfma_f32_32x32x16_bf16 v[82:97], v[98:101], v[146:149], v[66:81]
	v_mfma_f32_32x32x16_bf16 v[98:113], v[114:117], v[146:149], v[66:81]
	ds_read_b128 v[114:117], v241 offset:16384
	v_mfma_f32_32x32x16_bf16 v[82:97], v[118:121], v[150:153], v[82:97]
	ds_read_b128 v[118:121], v241 offset:24576
	s_waitcnt lgkmcnt(0)
	v_mfma_f32_32x32x16_bf16 v[98:113], v[122:125], v[150:153], v[98:113]
	ds_read_b128 v[122:125], v242 offset:16384
	v_mfma_f32_32x32x16_bf16 v[82:97], v[114:117], v[154:157], v[82:97]
	ds_read_b128 v[114:117], v242 offset:24576
	v_mfma_f32_32x32x16_bf16 v[98:113], v[118:121], v[154:157], v[98:113]
	s_waitcnt lgkmcnt(0)
	v_mfma_f32_32x32x16_bf16 v[82:97], v[122:125], v[158:161], v[82:97]
	v_mfma_f32_32x32x16_bf16 v[98:113], v[114:117], v[158:161], v[98:113]
	s_nop 0
	ds_read_b128 v[122:125], v245 offset:20480
	ds_read_b128 v[118:121], v245 offset:24576
	ds_read_b128 v[114:117], v245 offset:28672
	s_add_i32 s26, s20, 64
	s_cmp_le_u32 s26, s16
	s_cbranch_scc0 .Lr1u2_Lnear_u2o

.Lr2u2_LBB0_288:
	ds_read_b128 v[126:129], v245 offset:32768
	s_waitcnt lgkmcnt(1)
	v_mfma_f32_32x32x16_bf16 v[82:97], v[98:101], v[146:149], v[66:81]
	v_mfma_f32_32x32x16_bf16 v[98:113], v[114:117], v[146:149], v[66:81]
	ds_read_b128 v[114:117], v241 offset:32768
	v_mfma_f32_32x32x16_bf16 v[82:97], v[118:121], v[150:153], v[82:97]
	ds_read_b128 v[118:121], v241 offset:40960
	s_waitcnt lgkmcnt(0)
	v_mfma_f32_32x32x16_bf16 v[98:113], v[122:125], v[150:153], v[98:113]
	ds_read_b128 v[122:125], v242 offset:32768
	v_mfma_f32_32x32x16_bf16 v[82:97], v[114:117], v[154:157], v[82:97]
	ds_read_b128 v[114:117], v242 offset:40960
	v_mfma_f32_32x32x16_bf16 v[98:113], v[118:121], v[154:157], v[98:113]
	s_waitcnt lgkmcnt(0)
	v_mfma_f32_32x32x16_bf16 v[82:97], v[122:125], v[158:161], v[82:97]
	v_mfma_f32_32x32x16_bf16 v[98:113], v[114:117], v[158:161], v[98:113]
	s_nop 0
	ds_read_b128 v[122:125], v245 offset:36864
	ds_read_b128 v[118:121], v245 offset:40960
	ds_read_b128 v[114:117], v245 offset:45056
	s_cmp_le_u32 s20, s16
	s_cbranch_scc0 .Lr2u2_Lnear_u2e

.Lr2u2_LBB0_328:
	ds_read_b128 v[126:129], v245 offset:49152
	s_waitcnt lgkmcnt(1)
	v_mfma_f32_32x32x16_bf16 v[82:97], v[98:101], v[146:149], v[66:81]
	v_mfma_f32_32x32x16_bf16 v[98:113], v[114:117], v[146:149], v[66:81]
	ds_read_b128 v[114:117], v241
	v_mfma_f32_32x32x16_bf16 v[82:97], v[118:121], v[150:153], v[82:97]
	ds_read_b128 v[118:121], v241 offset:8192
	s_waitcnt lgkmcnt(0)
	v_mfma_f32_32x32x16_bf16 v[98:113], v[122:125], v[150:153], v[98:113]
	ds_read_b128 v[122:125], v242
	v_mfma_f32_32x32x16_bf16 v[82:97], v[114:117], v[154:157], v[82:97]
	ds_read_b128 v[114:117], v242 offset:8192
	v_mfma_f32_32x32x16_bf16 v[98:113], v[118:121], v[154:157], v[98:113]
	s_waitcnt lgkmcnt(0)
	v_mfma_f32_32x32x16_bf16 v[82:97], v[122:125], v[158:161], v[82:97]
	v_mfma_f32_32x32x16_bf16 v[98:113], v[114:117], v[158:161], v[98:113]
	s_nop 0
	ds_read_b128 v[122:125], v245 offset:53248
	ds_read_b128 v[118:121], v245 offset:57344
	ds_read_b128 v[114:117], v245 offset:61440
	s_add_i32 s26, s20, 64
	s_cmp_le_u32 s26, s16
	s_cbranch_scc0 .Lr2u2_Lnear_u2o
